# attention latent loops: K/V fragment LDS reads issued ahead of the MFMAs with counted lgkmcnt; pool unit: 5 window-row loads in flight, 4 taps per window-sum trip; mix1 unit-list swap moved to after r
# speedup vs baseline: 1.0199x; 1.0080x over previous
.LBB0_130:
	s_cmpk_lt_u32 s25, 0x200
	s_cbranch_scc1 .Lmix1_norebal
	s_cmpk_gt_u32 s25, 0x3ff
	s_cbranch_scc1 .Lmix1_norebal
	v_readlane_b32 s4, v253, 50
	s_nop 0
	s_cmpk_lg_u32 s4, 0x200
	s_cbranch_scc1 .Lmix1_norebal
	s_cmpk_lt_u32 s25, 0x300
	s_movk_i32 s0, 0x100
	s_cselect_b32 s0, s0, 0xffffff00
	s_add_i32 s25, s25, s0
	v_readlane_b32 s4, v255, 58
	s_lshl_b32 s5, s0, 4
	s_add_i32 s4, s4, s5
	s_nop 0
	v_writelane_b32 v255, s4, 58
	s_nop 0
	v_readlane_b32 s4, v255, 57
	s_lshl_b32 s5, s0, 6
	s_add_i32 s4, s4, s5
	s_nop 0
	v_writelane_b32 v255, s4, 57
	s_nop 0
	v_readlane_b32 s4, v255, 56
	s_add_i32 s4, s4, s0
	s_nop 0
	v_writelane_b32 v255, s4, 56
	s_nop 0
	v_readlane_b32 s4, v255, 55
	s_add_i32 s4, s4, s0
	s_nop 0
	v_writelane_b32 v255, s4, 55
	s_nop 0

.LBB0_131:
	s_bfe_u32 s40, s25, 0x20004
	v_writelane_b32 v255, s6, 58
	s_cmpk_gt_i32 s25, 0xff
	s_mov_b64 s[4:5], -1
	s_cbranch_scc0 .LBB0_195
	s_cmpk_gt_u32 s25, 0x1ff
	s_cbranch_scc0 .LBB0_168
	s_cmpk_gt_u32 s25, 0x2ff
	s_cbranch_scc0 .LBB0_162
	s_cmpk_gt_u32 s25, 0x4ff
	s_cbranch_scc0 .LBB0_156
	s_cmpk_gt_u32 s25, 0x6ff
	s_cbranch_scc0 .LBB0_153
	s_cmpk_gt_u32 s25, 0x8ff
	s_cbranch_scc0 .LBB0_150
	s_add_i32 s0, s25, 0xfffff700
	s_lshl_b32 s6, s0, 4
	s_and_b32 s14, s25, 3
	s_and_b32 s4, s6, 0x7fffffc0
	s_cmpk_gt_u32 s0, 0x1ff
	s_movk_i32 s0, 0x100
	s_cselect_b32 s5, 0x400, s0
	s_movk_i32 s0, 0x3c00
	s_cselect_b32 s0, s0, 0x1f00
	s_and_b32 s12, s0, s6
	v_mov_b32_e32 v8, v171
	s_movk_i32 s0, 0x500
	s_sub_i32 s13, s4, s12
	s_nop 0
	v_cmp_gt_i32_e32 vcc, s0, v8
	v_lshlrev_b32_e32 v9, 3, v8
	s_barrier
	s_lshl_b32 s0, s14, 8
	s_add_i32 s15, s13, -8
	v_readlane_b32 s16, v254, 4
	v_readlane_b32 s17, v254, 5
	v_lshlrev_b32_e32 v0, 4, v8
	v_and_b32_e32 v168, 0xf0, v0
	v_ashrrev_i32_e32 v2, 4, v8
	s_add_u32 s16, s16, s0
	s_addc_u32 s17, s17, 0
	s_add_u32 s16, s16, 0x1820
	s_addc_u32 s17, s17, 0
	s_add_i32 s10, s5, -1
	s_movk_i32 s11, 0x110
	v_add_u32_e32 v3, s15, v2
	v_mad_u32_u24 v11, v2, s11, v168
	v_add_u32_e32 v4, 0, v3
	v_max_i32_e32 v4, 0, v4
	v_min_i32_e32 v4, s10, v4
	v_add_u32_e32 v4, s12, v4
	v_mul_u32_u24_e32 v4, 0x3020, v4
	v_add_u32_e32 v4, v4, v168
	global_load_dwordx4 v[12:15], v4, s[16:17]
	v_add_u32_e32 v5, 16, v3
	v_max_i32_e32 v5, 0, v5
	v_min_i32_e32 v5, s10, v5
	v_add_u32_e32 v5, s12, v5
	v_mul_u32_u24_e32 v5, 0x3020, v5
	v_add_u32_e32 v5, v5, v168
	global_load_dwordx4 v[16:19], v5, s[16:17]
	v_add_u32_e32 v6, 32, v3
	v_max_i32_e32 v6, 0, v6
	v_min_i32_e32 v6, s10, v6
	v_add_u32_e32 v6, s12, v6
	v_mul_u32_u24_e32 v6, 0x3020, v6
	v_add_u32_e32 v6, v6, v168
	global_load_dwordx4 v[20:23], v6, s[16:17]
	v_add_u32_e32 v7, 48, v3
	v_max_i32_e32 v7, 0, v7
	v_min_i32_e32 v7, s10, v7
	v_add_u32_e32 v7, s12, v7
	v_mul_u32_u24_e32 v7, 0x3020, v7
	v_add_u32_e32 v7, v7, v168
	global_load_dwordx4 v[24:27], v7, s[16:17]
	v_add_u32_e32 v10, 64, v3
	v_max_i32_e32 v10, 0, v10
	v_min_i32_e32 v10, s10, v10
	v_add_u32_e32 v10, s12, v10
	v_mul_u32_u24_e32 v10, 0x3020, v10
	v_add_u32_e32 v10, v10, v168
	global_load_dwordx4 v[28:31], v10, s[16:17]
	s_waitcnt vmcnt(4)
	ds_write_b128 v11, v[12:15]
	s_waitcnt vmcnt(3)
	ds_write_b128 v11, v[16:19] offset:4352
	s_waitcnt vmcnt(2)
	ds_write_b128 v11, v[20:23] offset:8704
	s_waitcnt vmcnt(1)
	ds_write_b128 v11, v[24:27] offset:13056
	s_waitcnt vmcnt(0)
	ds_write_b128 v11, v[28:31] offset:17408
	s_movk_i32 s0, 0x400
	v_cmp_gt_i32_e32 vcc, s0, v8
	s_waitcnt lgkmcnt(0)
	s_barrier
	s_and_saveexec_b64 s[6:7], vcc
	s_cbranch_execz .LBB0_149
	v_readlane_b32 s3, v255, 58
	s_lshl_b32 s0, 2, s14
	s_and_b32 s8, s3, 0x7fffffc0
	s_lshr_b32 s9, s0, 1
	s_sub_i32 s16, s12, s8
	s_sub_i32 s8, s8, s12
	s_sub_i32 s15, s13, s9
	s_sub_i32 s17, s8, s9
	s_mov_b64 s[8:9], 0
	v_mov_b32_e32 v10, v8
	s_branch .LBB0_146

.LBB0_148:
	ds_read_b128 v[16:19], v14
	ds_read_b128 v[32:35], v14 offset:272
	ds_read_b128 v[36:39], v14 offset:544
	ds_read_b128 v[40:43], v14 offset:816
	s_waitcnt lgkmcnt(3)
	v_cvt_f32_f16_sdwa v21, v16 dst_sel:DWORD dst_unused:UNUSED_PAD src0_sel:WORD_1
	v_cvt_f32_f16_sdwa v23, v17 dst_sel:DWORD dst_unused:UNUSED_PAD src0_sel:WORD_1
	v_cvt_f32_f16_sdwa v25, v18 dst_sel:DWORD dst_unused:UNUSED_PAD src0_sel:WORD_1
	v_cvt_f32_f16_sdwa v27, v19 dst_sel:DWORD dst_unused:UNUSED_PAD src0_sel:WORD_1
	v_cvt_f32_f16_e32 v26, v19
	v_cvt_f32_f16_e32 v24, v18
	v_cvt_f32_f16_e32 v22, v17
	v_cvt_f32_f16_e32 v20, v16
	v_pk_add_f32 v[0:1], v[0:1], v[26:27]
	v_pk_add_f32 v[2:3], v[2:3], v[24:25]
	v_pk_add_f32 v[4:5], v[4:5], v[22:23]
	v_pk_add_f32 v[6:7], v[6:7], v[20:21]
	v_add_u32_e32 v15, 1, v15
	v_cmp_ge_i32_e32 vcc, v15, v13
	s_or_b64 s[12:13], vcc, s[12:13]
	s_andn2_b64 exec, exec, s[12:13]
	s_waitcnt lgkmcnt(2)
	v_cvt_f32_f16_sdwa v21, v32 dst_sel:DWORD dst_unused:UNUSED_PAD src0_sel:WORD_1
	v_cvt_f32_f16_sdwa v23, v33 dst_sel:DWORD dst_unused:UNUSED_PAD src0_sel:WORD_1
	v_cvt_f32_f16_sdwa v25, v34 dst_sel:DWORD dst_unused:UNUSED_PAD src0_sel:WORD_1
	v_cvt_f32_f16_sdwa v27, v35 dst_sel:DWORD dst_unused:UNUSED_PAD src0_sel:WORD_1
	v_cvt_f32_f16_e32 v26, v35
	v_cvt_f32_f16_e32 v24, v34
	v_cvt_f32_f16_e32 v22, v33
	v_cvt_f32_f16_e32 v20, v32
	v_pk_add_f32 v[0:1], v[0:1], v[26:27]
	v_pk_add_f32 v[2:3], v[2:3], v[24:25]
	v_pk_add_f32 v[4:5], v[4:5], v[22:23]
	v_pk_add_f32 v[6:7], v[6:7], v[20:21]
	v_add_u32_e32 v15, 1, v15
	v_cmp_ge_i32_e32 vcc, v15, v13
	s_or_b64 s[12:13], vcc, s[12:13]
	s_andn2_b64 exec, exec, s[12:13]
	s_waitcnt lgkmcnt(1)
	v_cvt_f32_f16_sdwa v21, v36 dst_sel:DWORD dst_unused:UNUSED_PAD src0_sel:WORD_1
	v_cvt_f32_f16_sdwa v23, v37 dst_sel:DWORD dst_unused:UNUSED_PAD src0_sel:WORD_1
	v_cvt_f32_f16_sdwa v25, v38 dst_sel:DWORD dst_unused:UNUSED_PAD src0_sel:WORD_1
	v_cvt_f32_f16_sdwa v27, v39 dst_sel:DWORD dst_unused:UNUSED_PAD src0_sel:WORD_1
	v_cvt_f32_f16_e32 v26, v39
	v_cvt_f32_f16_e32 v24, v38
	v_cvt_f32_f16_e32 v22, v37
	v_cvt_f32_f16_e32 v20, v36
	v_pk_add_f32 v[0:1], v[0:1], v[26:27]
	v_pk_add_f32 v[2:3], v[2:3], v[24:25]
	v_pk_add_f32 v[4:5], v[4:5], v[22:23]
	v_pk_add_f32 v[6:7], v[6:7], v[20:21]
	v_add_u32_e32 v15, 1, v15
	v_cmp_ge_i32_e32 vcc, v15, v13
	s_or_b64 s[12:13], vcc, s[12:13]
	s_andn2_b64 exec, exec, s[12:13]
	s_waitcnt lgkmcnt(0)
	v_cvt_f32_f16_sdwa v21, v40 dst_sel:DWORD dst_unused:UNUSED_PAD src0_sel:WORD_1
	v_cvt_f32_f16_sdwa v23, v41 dst_sel:DWORD dst_unused:UNUSED_PAD src0_sel:WORD_1
	v_cvt_f32_f16_sdwa v25, v42 dst_sel:DWORD dst_unused:UNUSED_PAD src0_sel:WORD_1
	v_cvt_f32_f16_sdwa v27, v43 dst_sel:DWORD dst_unused:UNUSED_PAD src0_sel:WORD_1
	v_cvt_f32_f16_e32 v26, v43
	v_cvt_f32_f16_e32 v24, v42
	v_cvt_f32_f16_e32 v22, v41
	v_cvt_f32_f16_e32 v20, v40
	v_pk_add_f32 v[0:1], v[0:1], v[26:27]
	v_pk_add_f32 v[2:3], v[2:3], v[24:25]
	v_pk_add_f32 v[4:5], v[4:5], v[22:23]
	v_pk_add_f32 v[6:7], v[6:7], v[20:21]
	v_add_u32_e32 v15, 1, v15
	v_cmp_ge_i32_e32 vcc, v15, v13
	s_or_b64 s[12:13], vcc, s[12:13]
	s_andn2_b64 exec, exec, s[12:13]
	v_add_u32_e32 v14, 0x440, v14
	s_cbranch_execnz .LBB0_148
	s_branch .LBB0_144

.LBB0_190:
	s_cmp_lt_i32 s18, s41
	s_cselect_b64 vcc, -1, 0
	s_and_b32 s0, s18, 1
	s_mul_i32 s10, s0, 0x4400
	v_or_b32_e32 v82, s10, v110
	v_add_u32_e32 v82, v82, v115
	ds_read_b128 v[176:179], v82
	ds_read_b128 v[180:183], v82 offset:64
	ds_read_b128 v[184:187], v82 offset:128
	ds_read_b128 v[188:191], v82 offset:192
	ds_read_b128 v[192:195], v82 offset:4352
	ds_read_b128 v[196:199], v82 offset:4416
	ds_read_b128 v[200:203], v82 offset:4480
	ds_read_b128 v[204:207], v82 offset:4544
	ds_read_b128 v[222:225], v82 offset:8704
	ds_read_b128 v[226:229], v82 offset:8768
	ds_read_b128 v[230:233], v82 offset:8832
	ds_read_b128 v[234:237], v82 offset:8896
	ds_read_b128 v[238:241], v82 offset:13056
	ds_read_b128 v[242:245], v82 offset:13120
	ds_read_b128 v[246:249], v82 offset:13184
	ds_read_b128 v[152:155], v82 offset:13248
	s_nop 0
	s_nop 0
	v_mov_b32_e32 v81, s8
	v_cndmask_b32_e32 v81, v81, v111, vcc
	v_sub_u32_e32 v81, v81, v129
	v_add_u32_e32 v81, 0xffffff7f, v81
	v_add_u32_e32 v83, v81, v109
	s_movk_i32 s10, 0xfeff
	s_nop 0
	s_waitcnt lgkmcnt(15)
	v_mfma_f32_16x16x32_f16 v[132:135], v[176:179], v[28:31], 0
	v_cmp_gt_u32_e64 s[36:37], s10, v83
	s_and_b64 s[36:37], vcc, s[36:37]
	s_nop 0
	s_nop 0
	s_waitcnt lgkmcnt(14)
	v_mfma_f32_16x16x32_f16 v[132:135], v[180:183], v[32:35], v[132:135]
	s_nop 0
	v_add_u32_e32 v95, v116, v81
	v_add_u32_e32 v131, v117, v81
	s_mulk_i32 s0, 0x4800
	s_add_i32 s8, s8, 64
	v_add_u32_e32 v111, 64, v111
	s_nop 0
	s_waitcnt lgkmcnt(13)
	v_mfma_f32_16x16x32_f16 v[132:135], v[184:187], v[36:39], v[132:135]
	s_nop 0
	s_nop 0
	s_nop 0
	s_nop 0
	s_waitcnt lgkmcnt(12)
	v_mfma_f32_16x16x32_f16 v[132:135], v[188:191], v[40:43], v[132:135]
	s_nop 0
	s_nop 6
	v_mul_f32_e32 v83, 0x3db504f3, v133
	v_mul_f32_e32 v102, 0x3db504f3, v134
	s_nop 0
	s_waitcnt lgkmcnt(11)
	v_mfma_f32_16x16x32_f16 v[136:139], v[192:195], v[28:31], 0
	v_add_u32_e32 v133, v81, v90
	v_add_u32_e32 v134, v119, v81
	s_waitcnt lgkmcnt(10)
	v_mfma_f32_16x16x32_f16 v[136:139], v[196:199], v[32:35], v[136:139]
	s_nop 0
	s_nop 0
	s_waitcnt lgkmcnt(9)
	v_mfma_f32_16x16x32_f16 v[136:139], v[200:203], v[36:39], v[136:139]
	s_nop 0
	s_nop 0
	s_waitcnt lgkmcnt(8)
	v_mfma_f32_16x16x32_f16 v[136:139], v[204:207], v[40:43], v[136:139]
	s_nop 0
	s_nop 0
	s_waitcnt lgkmcnt(7)
	v_mfma_f32_16x16x32_f16 v[140:143], v[222:225], v[28:31], 0
	s_waitcnt lgkmcnt(6)
	v_mfma_f32_16x16x32_f16 v[140:143], v[226:229], v[32:35], v[140:143]
	s_nop 0
	s_nop 0
	s_waitcnt lgkmcnt(5)
	v_mfma_f32_16x16x32_f16 v[140:143], v[230:233], v[36:39], v[140:143]
	s_nop 0
	s_nop 0
	s_waitcnt lgkmcnt(4)
	v_mfma_f32_16x16x32_f16 v[140:143], v[234:237], v[40:43], v[140:143]
	s_nop 0
	s_nop 0
	s_waitcnt lgkmcnt(3)
	v_mfma_f32_16x16x32_f16 v[144:147], v[238:241], v[28:31], 0
	s_waitcnt lgkmcnt(2)
	v_mfma_f32_16x16x32_f16 v[144:147], v[242:245], v[32:35], v[144:147]
	s_nop 0
	s_nop 0
	s_waitcnt lgkmcnt(1)
	v_mfma_f32_16x16x32_f16 v[144:147], v[246:249], v[36:39], v[144:147]
	s_nop 0
	v_mul_f32_e32 v82, 0x3db504f3, v132
	v_cndmask_b32_e64 v82, v82, v217, s[36:37]
	v_cmp_gt_u32_e64 s[36:37], s10, v95
	s_and_b64 s[36:37], vcc, s[36:37]
	v_add_u32_e32 v132, v118, v81
	v_cndmask_b32_e64 v83, v83, v217, s[36:37]
	v_cmp_gt_u32_e64 s[36:37], s10, v131
	s_and_b64 s[36:37], vcc, s[36:37]
	v_mul_f32_e32 v131, 0x3db504f3, v135
	v_cndmask_b32_e64 v102, v102, v217, s[36:37]
	v_cmp_gt_u32_e64 s[36:37], s10, v132
	s_and_b64 s[36:37], vcc, s[36:37]
	v_mul_f32_e32 v132, 0x3db504f3, v136
	v_cndmask_b32_e64 v131, v131, v217, s[36:37]
	v_cmp_gt_u32_e64 s[36:37], s10, v133
	s_and_b64 s[36:37], vcc, s[36:37]
	v_mul_f32_e32 v133, 0x3db504f3, v137
	v_cndmask_b32_e64 v132, v132, v217, s[36:37]
	v_cmp_gt_u32_e64 s[36:37], s10, v134
	s_and_b64 s[36:37], vcc, s[36:37]
	v_add_u32_e32 v135, v120, v81
	v_cndmask_b32_e64 v133, v133, v217, s[36:37]
	v_cmp_gt_u32_e64 s[36:37], s10, v135
	v_mul_f32_e32 v134, 0x3db504f3, v138
	s_and_b64 s[36:37], vcc, s[36:37]
	v_add_u32_e32 v136, v121, v81
	v_cndmask_b32_e64 v134, v134, v217, s[36:37]
	v_cmp_gt_u32_e64 s[36:37], s10, v136
	v_mul_f32_e32 v135, 0x3db504f3, v139
	s_and_b64 s[36:37], vcc, s[36:37]
	v_add_u32_e32 v137, v81, v88
	v_cndmask_b32_e64 v135, v135, v217, s[36:37]
	v_cmp_gt_u32_e64 s[36:37], s10, v137
	v_mul_f32_e32 v136, 0x3db504f3, v140
	s_and_b64 s[36:37], vcc, s[36:37]
	v_add_u32_e32 v138, v122, v81
	v_cndmask_b32_e64 v136, v136, v217, s[36:37]
	v_cmp_gt_u32_e64 s[36:37], s10, v138
	v_mul_f32_e32 v137, 0x3db504f3, v141
	s_and_b64 s[36:37], vcc, s[36:37]
	v_add_u32_e32 v139, v123, v81
	v_cndmask_b32_e64 v137, v137, v217, s[36:37]
	v_cmp_gt_u32_e64 s[36:37], s10, v139
	s_nop 0
	s_waitcnt lgkmcnt(0)
	v_mfma_f32_16x16x32_f16 v[144:147], v[152:155], v[40:43], v[144:147]
	v_add3_u32 v156, v114, s0, v128
	ds_read_b64 v[176:177], v156 offset:34816
	ds_read_b64 v[178:179], v156 offset:34848
	ds_read_b64 v[180:181], v156 offset:37120
	ds_read_b64 v[182:183], v156 offset:37152
	ds_read_b64 v[184:185], v156 offset:39424
	ds_read_b64 v[186:187], v156 offset:39456
	ds_read_b64 v[188:189], v156 offset:41728
	ds_read_b64 v[190:191], v156 offset:41760
	ds_read_b64 v[192:193], v156 offset:44032
	ds_read_b64 v[194:195], v156 offset:44064
	ds_read_b64 v[196:197], v156 offset:46336
	ds_read_b64 v[198:199], v156 offset:46368
	ds_read_b64 v[200:201], v156 offset:48640
	ds_read_b64 v[202:203], v156 offset:48672
	ds_read_b64 v[204:205], v156 offset:50944
	ds_read_b64 v[206:207], v156 offset:50976
	v_mul_f32_e32 v138, 0x3db504f3, v142
	s_and_b64 s[36:37], vcc, s[36:37]
	v_add_u32_e32 v140, v124, v81
	v_cndmask_b32_e64 v138, v138, v217, s[36:37]
	v_cmp_gt_u32_e64 s[36:37], s10, v140
	v_mul_f32_e32 v139, 0x3db504f3, v143
	s_and_b64 s[36:37], vcc, s[36:37]
	v_add_u32_e32 v141, v81, v86
	v_cndmask_b32_e64 v139, v139, v217, s[36:37]
	v_cmp_gt_u32_e64 s[36:37], s10, v141
	v_mul_f32_e32 v140, 0x3db504f3, v144
	s_and_b64 s[36:37], vcc, s[36:37]
	v_add_u32_e32 v142, v125, v81
	v_max3_f32 v95, v82, s2, v83
	v_cndmask_b32_e64 v140, v140, v217, s[36:37]
	v_cmp_gt_u32_e64 s[36:37], s10, v142
	v_max3_f32 v95, v95, v102, v131
	v_mul_f32_e32 v141, 0x3db504f3, v145
	s_and_b64 s[36:37], vcc, s[36:37]
	v_add_u32_e32 v143, v126, v81
	v_max3_f32 v95, v95, v132, v133
	v_cndmask_b32_e64 v141, v141, v217, s[36:37]
	v_cmp_gt_u32_e64 s[36:37], s10, v143
	v_max3_f32 v95, v95, v134, v135
	v_mul_f32_e32 v142, 0x3db504f3, v146
	s_and_b64 s[36:37], vcc, s[36:37]
	v_add_u32_e32 v81, v127, v81
	v_max3_f32 v95, v95, v136, v137
	v_cndmask_b32_e64 v142, v142, v217, s[36:37]
	v_cmp_gt_u32_e64 s[36:37], s10, v81
	v_max3_f32 v95, v95, v138, v139
	v_mul_f32_e32 v143, 0x3db504f3, v147
	s_and_b64 vcc, vcc, s[36:37]
	v_max3_f32 v95, v95, v140, v141
	v_cndmask_b32_e32 v81, v143, v217, vcc
	v_max3_f32 v95, v95, v142, v81
	ds_bpermute_b32 v143, v112, v95
	v_add3_u32 v148, v114, s0, v128
	v_add_u32_e32 v149, 0xa800, v148
	v_add_u32_e32 v150, 0xb000, v148
	v_add_u32_e32 v151, 0xb800, v148
	s_waitcnt lgkmcnt(0)
	v_max_f32_e32 v143, v143, v143
	v_max_f32_e32 v95, v95, v143
	ds_bpermute_b32 v143, v113, v95
	s_mov_b64 s[10:11], 0xc0800
	v_lshl_add_u64 v[100:101], v[100:101], 0, s[10:11]
	s_cmp_lg_u32 s16, s17
	s_waitcnt lgkmcnt(0)
	ds_read_b64 v[222:223], v156 offset:34880
	ds_read_b64 v[224:225], v156 offset:34912
	ds_read_b64 v[226:227], v156 offset:37184
	ds_read_b64 v[228:229], v156 offset:37216
	ds_read_b64 v[230:231], v156 offset:39488
	ds_read_b64 v[232:233], v156 offset:39520
	ds_read_b64 v[234:235], v156 offset:41792
	ds_read_b64 v[236:237], v156 offset:41824
	ds_read_b64 v[238:239], v156 offset:44096
	ds_read_b64 v[240:241], v156 offset:44128
	ds_read_b64 v[242:243], v156 offset:46400
	ds_read_b64 v[244:245], v156 offset:46432
	ds_read_b64 v[246:247], v156 offset:48704
	ds_read_b64 v[248:249], v156 offset:48736
	ds_read_b64 v[152:153], v156 offset:51008
	ds_read_b64 v[154:155], v156 offset:51040
	v_max3_f32 v95, v80, v95, v143
	v_sub_f32_e32 v83, v83, v95
	v_mul_f32_e32 v83, 0x3fb8aa3b, v83
	v_exp_f32_e32 v144, v83
	v_sub_f32_e32 v83, v102, v95
	v_mul_f32_e32 v83, 0x3fb8aa3b, v83
	v_exp_f32_e32 v145, v83
	v_sub_f32_e32 v83, v131, v95
	v_mul_f32_e32 v83, 0x3fb8aa3b, v83
	v_exp_f32_e32 v146, v83
	v_sub_f32_e32 v83, v132, v95
	v_mul_f32_e32 v83, 0x3fb8aa3b, v83
	v_sub_f32_e32 v82, v82, v95
	v_exp_f32_e32 v132, v83
	v_sub_f32_e32 v83, v133, v95
	v_sub_f32_e32 v102, v135, v95
	v_mul_f32_e32 v82, 0x3fb8aa3b, v82
	v_mul_f32_e32 v83, 0x3fb8aa3b, v83
	v_mul_f32_e32 v102, 0x3fb8aa3b, v102
	v_exp_f32_e32 v143, v82
	v_exp_f32_e32 v133, v83
	v_sub_f32_e32 v83, v134, v95
	v_exp_f32_e32 v134, v102
	v_sub_f32_e32 v102, v136, v95
	v_mul_f32_e32 v102, 0x3fb8aa3b, v102
	v_exp_f32_e32 v136, v102
	v_sub_f32_e32 v102, v137, v95
	v_mul_f32_e32 v102, 0x3fb8aa3b, v102
	v_add_f32_e32 v82, 0, v143
	v_exp_f32_e32 v137, v102
	v_sub_f32_e32 v102, v138, v95
	v_add_f32_e32 v82, v144, v82
	v_mul_f32_e32 v83, 0x3fb8aa3b, v83
	v_mul_f32_e32 v102, 0x3fb8aa3b, v102
	v_add_f32_e32 v82, v145, v82
	v_exp_f32_e32 v83, v83
	v_exp_f32_e32 v138, v102
	v_sub_f32_e32 v102, v139, v95
	v_add_f32_e32 v82, v146, v82
	v_mul_f32_e32 v102, 0x3fb8aa3b, v102
	v_add_f32_e32 v82, v132, v82
	v_exp_f32_e32 v139, v102
	v_sub_f32_e32 v102, v140, v95
	v_add_f32_e32 v82, v133, v82
	v_mul_f32_e32 v102, 0x3fb8aa3b, v102
	v_add_f32_e32 v82, v83, v82
	v_exp_f32_e32 v140, v102
	v_sub_f32_e32 v102, v141, v95
	v_add_f32_e32 v82, v134, v82
	v_mul_f32_e32 v102, 0x3fb8aa3b, v102
	v_add_f32_e32 v82, v136, v82
	v_exp_f32_e32 v141, v102
	v_sub_f32_e32 v102, v142, v95
	v_add_f32_e32 v82, v137, v82
	v_mul_f32_e32 v102, 0x3fb8aa3b, v102
	v_sub_f32_e32 v81, v81, v95
	v_add_f32_e32 v82, v138, v82
	v_exp_f32_e32 v142, v102
	v_mul_f32_e32 v81, 0x3fb8aa3b, v81
	v_add_f32_e32 v82, v139, v82
	v_exp_f32_e32 v147, v81
	v_sub_f32_e32 v80, v80, v95
	v_add_f32_e32 v82, v140, v82
	v_mul_f32_e32 v80, 0x3fb8aa3b, v80
	v_add_f32_e32 v82, v141, v82
	v_add_f32_e32 v82, v142, v82
	v_exp_f32_e32 v102, v80
	v_cvt_pk_f16_f32 v80, v143, v144
	v_add_u32_e32 v143, 0x8800, v148
	v_add_f32_e32 v131, v147, v82
	v_cvt_pk_f16_f32 v83, v83, v134
	v_cvt_pk_f16_f32 v82, v132, v133
	s_nop 0
	v_pk_mul_f32 v[46:47], v[46:47], v[102:103] op_sel_hi:[1,0]
	v_pk_mul_f32 v[44:45], v[44:45], v[102:103] op_sel_hi:[1,0]
	v_cvt_pk_f16_f32 v81, v145, v146
	v_add_u32_e32 v144, 0x9000, v148
	v_pk_mul_f32 v[26:27], v[26:27], v[102:103] op_sel_hi:[1,0]
	s_nop 0
	v_mfma_f32_16x16x32_f16 v[44:47], v[176:179], v[80:83], v[44:47]
	s_nop 0
	v_pk_mul_f32 v[24:25], v[24:25], v[102:103] op_sel_hi:[1,0]
	v_add_u32_e32 v145, 0x9800, v148
	v_pk_mul_f32 v[22:23], v[22:23], v[102:103] op_sel_hi:[1,0]
	s_nop 0
	v_mfma_f32_16x16x32_f16 v[24:27], v[180:183], v[80:83], v[24:27]
	s_nop 0
	v_pk_mul_f32 v[20:21], v[20:21], v[102:103] op_sel_hi:[1,0]
	v_add_u32_e32 v146, 0xa000, v148
	v_pk_mul_f32 v[18:19], v[18:19], v[102:103] op_sel_hi:[1,0]
	s_nop 0
	v_mfma_f32_16x16x32_f16 v[20:23], v[184:187], v[80:83], v[20:23]
	s_nop 0
	v_pk_mul_f32 v[16:17], v[16:17], v[102:103] op_sel_hi:[1,0]
	v_pk_mul_f32 v[14:15], v[14:15], v[102:103] op_sel_hi:[1,0]
	v_pk_mul_f32 v[12:13], v[12:13], v[102:103] op_sel_hi:[1,0]
	s_nop 0
	v_mfma_f32_16x16x32_f16 v[16:19], v[188:191], v[80:83], v[16:19]
	s_nop 0
	v_pk_mul_f32 v[10:11], v[10:11], v[102:103] op_sel_hi:[1,0]
	v_pk_mul_f32 v[8:9], v[8:9], v[102:103] op_sel_hi:[1,0]
	s_nop 0
	v_mfma_f32_16x16x32_f16 v[12:15], v[192:195], v[80:83], v[12:15]
	s_nop 0
	v_pk_mul_f32 v[6:7], v[6:7], v[102:103] op_sel_hi:[1,0]
	v_pk_mul_f32 v[4:5], v[4:5], v[102:103] op_sel_hi:[1,0]
	s_nop 0
	v_mfma_f32_16x16x32_f16 v[8:11], v[196:199], v[80:83], v[8:11]
	s_nop 0
	v_add_u32_e32 v148, 0xc000, v148
	v_pk_mul_f32 v[2:3], v[2:3], v[102:103] op_sel_hi:[1,0]
	s_nop 0
	v_mfma_f32_16x16x32_f16 v[4:7], v[200:203], v[80:83], v[4:7]
	s_nop 0
	v_pk_mul_f32 v[0:1], v[0:1], v[102:103] op_sel_hi:[1,0]
	v_fmac_f32_e32 v131, v130, v102
	s_nop 0
	v_mfma_f32_16x16x32_f16 v[0:3], v[204:207], v[80:83], v[0:3]
	s_nop 0
	v_cvt_pk_f16_f32 v83, v142, v147
	v_cvt_pk_f16_f32 v82, v140, v141
	v_cvt_pk_f16_f32 v81, v138, v139
	v_cvt_pk_f16_f32 v80, v136, v137
	s_nop 0
	s_nop 0
	s_waitcnt lgkmcnt(0)
	v_mfma_f32_16x16x32_f16 v[44:47], v[222:225], v[80:83], v[44:47]
	s_nop 0
	s_nop 0
	v_mfma_f32_16x16x32_f16 v[24:27], v[226:229], v[80:83], v[24:27]
	s_nop 0
	s_nop 0
	v_mfma_f32_16x16x32_f16 v[20:23], v[230:233], v[80:83], v[20:23]
	s_nop 0
	s_nop 0
	v_mfma_f32_16x16x32_f16 v[16:19], v[234:237], v[80:83], v[16:19]
	s_nop 0
	s_nop 0
	v_mfma_f32_16x16x32_f16 v[12:15], v[238:241], v[80:83], v[12:15]
	s_nop 0
	s_nop 0
	v_mfma_f32_16x16x32_f16 v[8:11], v[242:245], v[80:83], v[8:11]
	s_nop 0
	s_nop 0
	v_mfma_f32_16x16x32_f16 v[4:7], v[246:249], v[80:83], v[4:7]
	s_nop 0
	s_waitcnt lgkmcnt(0)
	s_barrier
	v_mfma_f32_16x16x32_f16 v[0:3], v[152:155], v[80:83], v[0:3]
	s_cbranch_scc1 .LBB0_183
	v_mov_b32_e32 v81, v215
	v_mov_b32_e32 v80, v109
	s_branch .LBB0_193

.LBB0_208:
	s_cmp_lt_u32 s19, 8
	s_cselect_b64 vcc, -1, 0
	v_mov_b32_e32 v17, s0
	s_and_b32 s0, s19, 1
	s_mul_i32 s9, s0, 0x4400
	v_or_b32_e32 v30, s9, v122
	v_add_u32_e32 v146, v30, v113
	ds_read_b128 v[176:179], v146
	ds_read_b128 v[180:183], v146 offset:64
	ds_read_b128 v[184:187], v146 offset:128
	ds_read_b128 v[188:191], v146 offset:192
	ds_read_b128 v[192:195], v146 offset:4352
	ds_read_b128 v[196:199], v146 offset:4416
	ds_read_b128 v[200:203], v146 offset:4480
	ds_read_b128 v[204:207], v146 offset:4544
	ds_read_b128 v[222:225], v146 offset:8704
	ds_read_b128 v[226:229], v146 offset:8768
	ds_read_b128 v[230:233], v146 offset:8832
	ds_read_b128 v[234:237], v146 offset:8896
	ds_read_b128 v[238:241], v146 offset:13056
	ds_read_b128 v[242:245], v146 offset:13120
	ds_read_b128 v[246:249], v146 offset:13184
	ds_read_b128 v[152:155], v146 offset:13248
	s_nop 0
	s_nop 0
	v_add_u32_e32 v16, s18, v109
	v_cndmask_b32_e64 v16, v17, v16, s[84:85]
	s_nop 0
	v_ashrrev_i32_e32 v17, 31, v16
	v_lshlrev_b64 v[16:17], 1, v[16:17]
	s_nop 0
	s_waitcnt lgkmcnt(15)
	v_mfma_f32_16x16x32_f16 v[32:35], v[176:179], v[12:15], 0
	v_lshl_add_u64 v[96:97], s[12:13], 0, v[16:17]
	v_mad_i64_i32 v[16:17], s[12:13], s10, v106, 0
	v_mad_i64_i32 v[20:21], s[12:13], s10, v110, 0
	v_mad_i64_i32 v[24:25], s[12:13], s10, v112, 0
	v_mad_i64_i32 v[30:31], s[10:11], s10, v114, 0
	v_mad_i64_i32 v[44:45], s[10:11], s8, v108, 0
	v_lshl_add_u64 v[80:81], v[44:45], 1, v[96:97]
	v_mov_b32_e32 v131, v169
	s_nop 0
	s_nop 0
	s_waitcnt lgkmcnt(14)
	v_mfma_f32_16x16x32_f16 v[36:39], v[180:183], v[8:11], v[32:35]
	v_lshl_add_u64 v[16:17], v[16:17], 1, v[28:29]
	v_lshl_add_u64 v[20:21], v[20:21], 1, v[28:29]
	v_lshl_add_u64 v[24:25], v[24:25], 1, v[28:29]
	v_lshl_add_u64 v[32:33], v[80:81], 0, v[130:131]
	s_nop 0
	s_nop 0
	s_waitcnt lgkmcnt(13)
	v_mfma_f32_16x16x32_f16 v[36:39], v[184:187], v[4:7], v[36:39]
	v_mad_i64_i32 v[40:41], s[10:11], s8, v116, 0
	v_lshl_add_u64 v[84:85], v[40:41], 1, v[96:97]
	s_nop 0
	s_nop 0
	s_waitcnt lgkmcnt(12)
	v_mfma_f32_16x16x32_f16 v[88:91], v[188:191], v[0:3], v[36:39]
	v_lshl_add_u64 v[28:29], v[30:31], 1, v[28:29]
	v_lshl_add_u64 v[16:17], v[16:17], 0, v[168:169]
	v_lshl_add_u64 v[20:21], v[20:21], 0, v[168:169]
	s_nop 0
	s_waitcnt lgkmcnt(11)
	v_mfma_f32_16x16x32_f16 v[44:47], v[192:195], v[12:15], 0
	s_nop 0
	v_lshl_add_u64 v[36:37], v[84:85], 0, v[130:131]
	v_mad_i64_i32 v[84:85], s[10:11], s8, v118, 0
	v_lshl_add_u64 v[92:93], v[84:85], 1, v[96:97]
	s_nop 0
	s_nop 0
	s_waitcnt lgkmcnt(10)
	v_mfma_f32_16x16x32_f16 v[44:47], v[196:199], v[8:11], v[44:47]
	v_lshl_add_u64 v[24:25], v[24:25], 0, v[168:169]
	v_lshl_add_u64 v[28:29], v[28:29], 0, v[168:169]
	v_lshl_add_u64 v[40:41], v[92:93], 0, v[130:131]
	s_nop 0
	s_waitcnt lgkmcnt(9)
	v_mfma_f32_16x16x32_f16 v[44:47], v[200:203], v[4:7], v[44:47]
	v_mad_i64_i32 v[80:81], s[8:9], s8, v120, 0
	v_lshl_add_u64 v[80:81], v[80:81], 1, v[96:97]
	s_nop 0
	s_waitcnt lgkmcnt(8)
	v_mfma_f32_16x16x32_f16 v[84:87], v[204:207], v[0:3], v[44:47]
	global_load_dwordx4 v[16:19], v[16:17], off
	s_nop 0
	s_nop 0
	s_nop 0
	v_lshl_add_u64 v[44:45], v[80:81], 0, v[130:131]
	global_load_dwordx4 v[20:23], v[20:21], off
	s_nop 0
	s_waitcnt lgkmcnt(7)
	v_mfma_f32_16x16x32_f16 v[80:83], v[222:225], v[12:15], 0
	global_load_dwordx4 v[24:27], v[24:25], off
	s_nop 0
	global_load_dwordx4 v[28:31], v[28:29], off
	s_nop 0
	s_waitcnt lgkmcnt(6)
	v_mfma_f32_16x16x32_f16 v[80:83], v[226:229], v[8:11], v[80:83]
	global_load_dwordx4 v[32:35], v[32:33], off
	s_nop 0
	global_load_dwordx4 v[36:39], v[36:37], off
	s_nop 0
	s_waitcnt lgkmcnt(5)
	v_mfma_f32_16x16x32_f16 v[80:83], v[230:233], v[4:7], v[80:83]
	global_load_dwordx4 v[40:43], v[40:41], off
	s_nop 0
	global_load_dwordx4 v[44:47], v[44:45], off
	s_nop 0
	s_waitcnt lgkmcnt(4)
	v_mfma_f32_16x16x32_f16 v[80:83], v[234:237], v[0:3], v[80:83]
	s_nop 0
	v_mov_b32_e32 v131, 0xfffffe00
	v_cndmask_b32_e32 v131, v131, v104, vcc
	s_nop 0
	s_waitcnt lgkmcnt(3)
	v_mfma_f32_16x16x32_f16 v[92:95], v[238:241], v[12:15], 0
	v_add_u32_e32 v131, s18, v131
	s_movk_i32 s8, 0x7c
	v_mul_f32_e32 v88, 0x3db504f3, v88
	s_waitcnt lgkmcnt(2)
	v_mfma_f32_16x16x32_f16 v[92:95], v[242:245], v[8:11], v[92:95]
	s_nop 0
	s_and_b64 s[10:11], vcc, s[36:37]
	s_nop 0
	s_waitcnt lgkmcnt(1)
	v_mfma_f32_16x16x32_f16 v[92:95], v[246:249], v[4:7], v[92:95]
	s_nop 0
	s_nop 0
	s_waitcnt lgkmcnt(0)
	v_mfma_f32_16x16x32_f16 v[92:95], v[152:155], v[0:3], v[92:95]
	v_mov_b32_e32 v157, 0x4800
	v_mul_u32_u24_e32 v157, s0, v157
	v_add3_u32 v156, v105, v157, v107
	ds_read_b64 v[176:177], v156 offset:34816
	ds_read_b64 v[178:179], v156 offset:34848
	ds_read_b64 v[180:181], v156 offset:37120
	ds_read_b64 v[182:183], v156 offset:37152
	ds_read_b64 v[184:185], v156 offset:39424
	ds_read_b64 v[186:187], v156 offset:39456
	ds_read_b64 v[188:189], v156 offset:41728
	ds_read_b64 v[190:191], v156 offset:41760
	ds_read_b64 v[192:193], v156 offset:44032
	ds_read_b64 v[194:195], v156 offset:44064
	ds_read_b64 v[196:197], v156 offset:46336
	ds_read_b64 v[198:199], v156 offset:46368
	ds_read_b64 v[200:201], v156 offset:48640
	ds_read_b64 v[202:203], v156 offset:48672
	ds_read_b64 v[204:205], v156 offset:50944
	ds_read_b64 v[206:207], v156 offset:50976
	v_ashrrev_i32_e32 v96, 6, v131
	v_subrev_u32_e32 v96, s15, v96
	v_mul_lo_u32 v96, v96, s8
	v_add_u32_e32 v97, 0x11800, v96
	v_cndmask_b32_e32 v96, v88, v217, vcc
	s_and_saveexec_b64 s[8:9], s[10:11]
	s_cbranch_execz .LBB0_210
	v_lshl_add_u32 v96, v121, 2, v97
	ds_read_b32 v96, v96 offset:928
	s_waitcnt lgkmcnt(0)
	v_add_f32_e32 v96, v88, v96

.LBB0_240:
	s_or_b64 exec, exec, s[8:9]
	v_max3_f32 v85, v96, s2, v89
	v_max3_f32 v85, v85, v90, v88
	v_max3_f32 v85, v85, v84, v91
	v_max3_f32 v85, v85, v86, v87
	v_max3_f32 v85, v85, v80, v81
	v_max3_f32 v85, v85, v82, v83
	v_max3_f32 v85, v85, v92, v93
	v_max3_f32 v85, v85, v94, v95
	ds_bpermute_b32 v97, v117, v85
	s_mulk_i32 s0, 0x4800
	s_add_i32 s18, s18, 64
	s_mov_b64 s[8:9], 0xc0800
	v_lshl_add_u64 v[128:129], v[128:129], 0, s[8:9]
	s_waitcnt lgkmcnt(0)
	v_max_f32_e32 v97, v97, v97
	v_max_f32_e32 v85, v85, v97
	ds_bpermute_b32 v97, v119, v85
	s_cmp_lg_u32 s14, 10
	s_waitcnt lgkmcnt(0)
	ds_read_b64 v[222:223], v156 offset:34880
	ds_read_b64 v[224:225], v156 offset:34912
	ds_read_b64 v[226:227], v156 offset:37184
	ds_read_b64 v[228:229], v156 offset:37216
	ds_read_b64 v[230:231], v156 offset:39488
	ds_read_b64 v[232:233], v156 offset:39520
	ds_read_b64 v[234:235], v156 offset:41792
	ds_read_b64 v[236:237], v156 offset:41824
	ds_read_b64 v[238:239], v156 offset:44096
	ds_read_b64 v[240:241], v156 offset:44128
	ds_read_b64 v[242:243], v156 offset:46400
	ds_read_b64 v[244:245], v156 offset:46432
	ds_read_b64 v[246:247], v156 offset:48704
	ds_read_b64 v[248:249], v156 offset:48736
	ds_read_b64 v[152:153], v156 offset:51008
	ds_read_b64 v[154:155], v156 offset:51040
	v_max3_f32 v85, v145, v85, v97
	v_sub_f32_e32 v96, v96, v85
	v_mul_f32_e32 v96, 0x3fb8aa3b, v96
	v_sub_f32_e32 v89, v89, v85
	v_exp_f32_e32 v96, v96
	v_mul_f32_e32 v89, 0x3fb8aa3b, v89
	v_sub_f32_e32 v90, v90, v85
	v_exp_f32_e32 v89, v89
	v_mul_f32_e32 v90, 0x3fb8aa3b, v90
	v_sub_f32_e32 v88, v88, v85
	v_exp_f32_e32 v90, v90
	v_mul_f32_e32 v88, 0x3fb8aa3b, v88
	v_sub_f32_e32 v84, v84, v85
	v_sub_f32_e32 v81, v81, v85
	v_exp_f32_e32 v88, v88
	v_mul_f32_e32 v84, 0x3fb8aa3b, v84
	v_mul_f32_e32 v81, 0x3fb8aa3b, v81
	v_sub_f32_e32 v97, v145, v85
	v_add_f32_e32 v98, 0, v96
	v_exp_f32_e32 v99, v84
	v_sub_f32_e32 v91, v91, v85
	v_exp_f32_e32 v145, v81
	v_sub_f32_e32 v81, v82, v85
	v_add_f32_e32 v98, v89, v98
	v_mul_f32_e32 v91, 0x3fb8aa3b, v91
	v_sub_f32_e32 v86, v86, v85
	v_mul_f32_e32 v81, 0x3fb8aa3b, v81
	v_add_f32_e32 v98, v90, v98
	v_exp_f32_e32 v91, v91
	v_mul_f32_e32 v86, 0x3fb8aa3b, v86
	v_sub_f32_e32 v87, v87, v85
	v_exp_f32_e32 v146, v81
	v_sub_f32_e32 v81, v83, v85
	v_add_f32_e32 v98, v88, v98
	v_exp_f32_e32 v86, v86
	v_mul_f32_e32 v87, 0x3fb8aa3b, v87
	v_sub_f32_e32 v80, v80, v85
	v_mul_f32_e32 v81, 0x3fb8aa3b, v81
	v_add_f32_e32 v84, v99, v98
	v_exp_f32_e32 v98, v87
	v_mul_f32_e32 v80, 0x3fb8aa3b, v80
	v_exp_f32_e32 v147, v81
	v_sub_f32_e32 v81, v92, v85
	v_exp_f32_e32 v131, v80
	v_mul_f32_e32 v81, 0x3fb8aa3b, v81
	v_add_f32_e32 v84, v91, v84
	v_exp_f32_e32 v92, v81
	v_sub_f32_e32 v81, v93, v85
	v_add_f32_e32 v84, v86, v84
	v_mul_f32_e32 v81, 0x3fb8aa3b, v81
	v_add_f32_e32 v84, v98, v84
	v_exp_f32_e32 v93, v81
	v_sub_f32_e32 v81, v94, v85
	v_add_f32_e32 v80, v131, v84
	v_mul_f32_e32 v81, 0x3fb8aa3b, v81
	v_mul_f32_e32 v97, 0x3fb8aa3b, v97
	v_add_f32_e32 v80, v145, v80
	v_exp_f32_e32 v94, v81
	v_sub_f32_e32 v81, v95, v85
	v_add_f32_e32 v80, v146, v80
	v_mul_f32_e32 v81, 0x3fb8aa3b, v81
	v_exp_f32_e32 v84, v97
	v_add_f32_e32 v80, v147, v80
	v_exp_f32_e32 v95, v81
	v_add_f32_e32 v80, v92, v80
	v_add_f32_e32 v80, v93, v80
	v_add3_u32 v97, v105, s0, v107
	v_add_f32_e32 v80, v94, v80
	v_pk_mul_f32 v[82:83], v[50:51], v[84:85] op_sel_hi:[1,0]
	v_pk_mul_f32 v[50:51], v[78:79], v[84:85] op_sel_hi:[1,0]
	v_cvt_pk_f16_f32 v79, v86, v98
	v_add_u32_e32 v86, 0x8800, v97
	v_add_f32_e32 v87, v95, v80
	v_pk_mul_f32 v[80:81], v[48:49], v[84:85] op_sel_hi:[1,0]
	v_pk_mul_f32 v[48:49], v[76:77], v[84:85] op_sel_hi:[1,0]
	v_cvt_pk_f16_f32 v78, v99, v91
	v_cvt_pk_f16_f32 v77, v90, v88
	v_cvt_pk_f16_f32 v76, v96, v89
	s_nop 0
	v_add_u32_e32 v96, 0x9000, v97
	s_nop 0
	v_mfma_f32_16x16x32_f16 v[88:91], v[176:179], v[76:79], v[80:83]
	s_nop 2
	s_nop 0
	v_pk_mul_f32 v[54:55], v[54:55], v[84:85] op_sel_hi:[1,0]
	v_pk_mul_f32 v[52:53], v[52:53], v[84:85] op_sel_hi:[1,0]
	v_add_u32_e32 v98, 0x9800, v97
	v_pk_mul_f32 v[58:59], v[58:59], v[84:85] op_sel_hi:[1,0]
	s_nop 0
	v_mfma_f32_16x16x32_f16 v[52:55], v[180:183], v[76:79], v[52:55]
	s_nop 0
	v_pk_mul_f32 v[56:57], v[56:57], v[84:85] op_sel_hi:[1,0]
	v_add_u32_e32 v99, 0xa000, v97
	v_pk_mul_f32 v[62:63], v[62:63], v[84:85] op_sel_hi:[1,0]
	s_nop 0
	v_mfma_f32_16x16x32_f16 v[56:59], v[184:187], v[76:79], v[56:59]
	s_nop 0
	v_pk_mul_f32 v[60:61], v[60:61], v[84:85] op_sel_hi:[1,0]
	v_add_u32_e32 v148, 0xa800, v97
	v_pk_mul_f32 v[66:67], v[66:67], v[84:85] op_sel_hi:[1,0]
	s_nop 0
	v_mfma_f32_16x16x32_f16 v[60:63], v[188:191], v[76:79], v[60:63]
	s_nop 0
	v_pk_mul_f32 v[64:65], v[64:65], v[84:85] op_sel_hi:[1,0]
	v_add_u32_e32 v149, 0xb000, v97
	v_pk_mul_f32 v[70:71], v[70:71], v[84:85] op_sel_hi:[1,0]
	s_nop 0
	v_mfma_f32_16x16x32_f16 v[64:67], v[192:195], v[76:79], v[64:67]
	s_nop 0
	v_pk_mul_f32 v[68:69], v[68:69], v[84:85] op_sel_hi:[1,0]
	v_add_u32_e32 v150, 0xb800, v97
	v_pk_mul_f32 v[74:75], v[74:75], v[84:85] op_sel_hi:[1,0]
	s_nop 0
	v_mfma_f32_16x16x32_f16 v[68:71], v[196:199], v[76:79], v[68:71]
	s_nop 0
	v_pk_mul_f32 v[72:73], v[72:73], v[84:85] op_sel_hi:[1,0]
	v_add_u32_e32 v97, 0xc000, v97
	v_fmac_f32_e32 v87, v144, v84
	s_nop 0
	v_mfma_f32_16x16x32_f16 v[72:75], v[200:203], v[76:79], v[72:75]
	s_nop 0
	s_nop 0
	v_mfma_f32_16x16x32_f16 v[76:79], v[204:207], v[76:79], v[48:51]
	s_nop 2
	s_nop 0
	v_cvt_pk_f16_f32 v83, v94, v95
	v_cvt_pk_f16_f32 v82, v92, v93
	v_cvt_pk_f16_f32 v81, v146, v147
	v_cvt_pk_f16_f32 v80, v131, v145
	s_nop 0
	s_nop 0
	s_waitcnt lgkmcnt(0)
	v_mfma_f32_16x16x32_f16 v[48:51], v[222:225], v[80:83], v[88:91]
	s_nop 2
	s_nop 0
	s_nop 0
	v_mfma_f32_16x16x32_f16 v[52:55], v[226:229], v[80:83], v[52:55]
	s_nop 0
	s_nop 0
	v_mfma_f32_16x16x32_f16 v[56:59], v[230:233], v[80:83], v[56:59]
	s_nop 0
	s_nop 0
	v_mfma_f32_16x16x32_f16 v[60:63], v[234:237], v[80:83], v[60:63]
	s_nop 0
	s_nop 0
	v_mfma_f32_16x16x32_f16 v[64:67], v[238:241], v[80:83], v[64:67]
	s_nop 0
	s_nop 0
	v_mfma_f32_16x16x32_f16 v[68:71], v[242:245], v[80:83], v[68:71]
	s_nop 0
	s_nop 0
	v_mfma_f32_16x16x32_f16 v[72:75], v[246:249], v[80:83], v[72:75]
	s_nop 0
	s_waitcnt lgkmcnt(0)
	s_barrier
	v_mfma_f32_16x16x32_f16 v[76:79], v[152:155], v[80:83], v[76:79]
	s_cbranch_scc0 .LBB0_129
	v_mov_b32_e32 v145, v85
	v_mov_b32_e32 v144, v87
	s_mov_b32 s19, s14
	s_branch .LBB0_205
